# in-proj round rotation per XCD, applied only when the grid is 256 workgroups (otherwise the original order)
# baseline (speedup 1.0000x reference)
.LBB0_771:
	v_add_u32_e32 v0, s76, v8
	s_cmpk_lt_i32 s78, 0xe00
	v_writelane_b32 v255, s80, 1
	v_readfirstlane_b32 s18, v0
	s_cselect_b64 s[40:41], -1, 0
	s_cmpk_gt_i32 s78, 0xdff
	v_mbcnt_lo_u32_b32 v0, -1, 0
	v_mbcnt_hi_u32_b32 v0, -1, v0
	s_cbranch_scc1 .LBB0_773
	s_and_b32 s5, s78, 7
	s_lshl_b32 s5, s5, 8
	s_cmp_eq_u32 s79, 0x100
	s_cselect_b32 s5, s5, 0
	s_add_i32 s5, s5, s78
	s_ashr_i32 s0, s5, 31
	s_lshr_b32 s0, s0, 29
	s_add_i32 s0, s5, s0
	s_ashr_i32 s1, s0, 3
	s_and_b32 s0, s0, -8
	s_sub_i32 s0, s5, s0
	s_cmp_lt_i32 s0, 0
	s_movk_i32 s4, 0x1c1
	s_cselect_b32 s4, s4, 0x1c0
	s_mul_i32 s0, s0, s4
	s_add_i32 s0, s0, s1
	s_mul_hi_i32 s1, s0, 0x92492493
	s_add_i32 s1, s1, s0
	s_lshr_b32 s4, s1, 31
	s_ashr_i32 s1, s1, 6
	s_add_i32 s1, s1, s4
	s_lshl_b32 s4, s1, 3
	s_mulk_i32 s1, 0x70
	s_sub_i32 s0, s0, s1
	s_bfe_i32 s1, s0, 0x80000
	s_bfe_u32 s1, s1, 0x3000c
	s_add_i32 s1, s0, s1
	s_bfe_i32 s5, s1, 0x80000
	s_and_b32 s1, s1, 0xf8
	s_sub_i32 s0, s0, s1
	s_sext_i32_i16 s5, s5
	s_sext_i32_i8 s0, s0
	s_add_i32 s4, s4, s0
	s_ashr_i32 s8, s5, 3

.LBB0_781:
	s_add_i32 s18, s5, 1
	s_cmp_eq_u32 s79, 0x100
	s_cbranch_scc0 .Lmy_inrot_generic
	s_and_b32 s9, s78, 7
	s_add_i32 s9, s9, s18
	s_cmp_ge_i32 s9, 14
	s_cselect_b32 s19, 14, 0
	s_sub_i32 s9, s9, s19
	s_mul_i32 s36, s9, s79
	s_add_u32 s36, s36, s78
	s_mov_b32 s37, 0
	s_cmp_lt_i32 s18, 14
	s_cselect_b64 s[38:39], -1, 0
	s_cselect_b64 vcc, 0, -1
	s_branch .Lmy_inrot_join
.Lmy_inrot_generic:
	s_mul_i32 s9, s18, s65
	s_mul_hi_u32 s19, s18, s79
	s_add_i32 s19, s19, s9
	s_mul_i32 s9, s18, s79
	s_add_u32 s36, s9, s78
	s_addc_u32 s37, s19, s61
	v_mov_b64_e32 v[0:1], 0xe00
	v_cmp_lt_i64_e64 s[38:39], s[36:37], v[0:1]
	v_mov_b64_e32 v[0:1], 0xdff
	v_cmp_gt_i64_e32 vcc, s[36:37], v[0:1]
.Lmy_inrot_join:
	s_cbranch_vccnz .LBB0_783
	s_ashr_i32 s9, s36, 31
	s_lshr_b32 s9, s9, 29
	s_add_i32 s9, s36, s9
	s_ashr_i32 s19, s9, 3
	s_and_b32 s9, s9, -8
	s_sub_i32 s9, s36, s9
	s_cmp_lt_i32 s9, 0
	s_movk_i32 s36, 0x1c1
	s_cselect_b32 s36, s36, 0x1c0
	s_mul_i32 s9, s9, s36
	s_add_i32 s9, s9, s19
	s_mul_hi_i32 s19, s9, 0x92492493
	s_add_i32 s19, s19, s9
	s_lshr_b32 s36, s19, 31
	s_ashr_i32 s19, s19, 6
	s_add_i32 s19, s19, s36
	s_lshl_b32 s36, s19, 3
	s_sub_i32 s37, 0x100, s36
	s_min_i32 s37, s37, 8
	s_abs_i32 s42, s37
	v_cvt_f32_u32_e32 v0, s42
	s_sub_i32 s68, 0, s42
	s_mulk_i32 s19, 0x70
	s_sub_i32 s9, s9, s19
	v_rcp_iflag_f32_e32 v0, v0
	s_abs_i32 s19, s9
	s_xor_b32 s43, s9, s37
	s_ashr_i32 s43, s43, 31
	v_mul_f32_e32 v0, 0x4f7ffffe, v0
	v_cvt_u32_f32_e32 v0, v0
	s_nop 0
	v_readfirstlane_b32 s69, v0
	s_mul_i32 s68, s68, s69
	s_mul_hi_u32 s68, s69, s68
	s_add_i32 s69, s69, s68
	s_mul_hi_u32 s68, s19, s69
	s_mul_i32 s69, s68, s42
	s_sub_i32 s19, s19, s69
	s_add_i32 s70, s68, 1
	s_sub_i32 s69, s19, s42
	s_cmp_ge_u32 s19, s42
	s_cselect_b32 s68, s70, s68
	s_cselect_b32 s19, s69, s19
	s_add_i32 s69, s68, 1
	s_cmp_ge_u32 s19, s42
	s_cselect_b32 s19, s69, s68
	s_xor_b32 s19, s19, s43
	s_sub_i32 s68, s19, s43
	s_mul_i32 s19, s68, s37
	s_sub_i32 s9, s9, s19
	s_add_i32 s70, s36, s9
